# MLA: first MFMA run after the tile barrier waits per fragment (counted lgkmcnt at each first consumer) instead of lgkmcnt(8) once
# speedup vs baseline: 1.0027x; 1.0027x over previous
; #define LAS __attribute__((address_space(3)))
; #define MFMA32(a, b, c) __builtin_amdgcn_mfma_f32_32x32x16_bf16((a), (b), (c), 0, 0, 0)
; DI void mla_pv(const LAS unsigned char* base, int r, int h, const bf16x8 (&pf0)[2], const bf16x8 (&pf1)[2], f32x16 (&o)[4]) {
;     const LAS unsigned char* vp = base + MLA_KBYTES + r * MLA_VROW + h * 32;
; #pragma unroll
;     for (int s = 0; s < 2; ++s) {
;         bf16x8 va[4], vb[4];
; #pragma unroll
;         for (int dt = 0; dt < 4; ++dt) { va[dt] = *(const LAS bf16x8*)(vp + dt * 32 * MLA_VROW + s * 16); vb[dt] = *(const LAS bf16x8*)(vp + dt * 32 * MLA_VROW + 64 + s * 16); }
;         __builtin_amdgcn_sched_barrier(0);
; #pragma unroll
;         for (int dt = 0; dt < 4; ++dt) o[dt] = MFMA32(va[dt], pf0[s], o[dt]);
; #pragma unroll
;         for (int dt = 0; dt < 4; ++dt) o[dt] = MFMA32(vb[dt], pf1[s], o[dt]);
;         __builtin_amdgcn_sched_barrier(0);
;     }
.LBB0_635:
	s_cmp_lg_u32 s77, 0
	s_cselect_b64 s[90:91], -1, 0
	s_and_b64 s[90:91], s[78:79], s[90:91]
	s_cmp_le_i32 s77, s84
	s_cselect_b64 vcc, -1, 0
	s_and_b64 s[90:91], s[90:91], vcc
	s_andn2_b64 vcc, exec, s[90:91]
	s_mul_i32 s89, s73, 0xac00
	s_cbranch_vccnz .LBB0_638
	s_add_i32 s90, s89, 0xffff5400
	s_cmp_lg_u32 s73, 0
	s_cselect_b32 s73, s90, 0x15800
	v_add_u32_e32 v0, s73, v182
	ds_read_b128 v[84:87], v0 offset:25600
	ds_read_b128 v[88:91], v0 offset:25664
	ds_read_b128 v[92:95], v0 offset:30208
	ds_read_b128 v[96:99], v0 offset:30272
	ds_read_b128 v[100:103], v0 offset:34816
	ds_read_b128 v[104:107], v0 offset:34880
	ds_read_b128 v[108:111], v0 offset:39424
	ds_read_b128 v[186:189], v0 offset:39488
	ds_read_b128 v[200:203], v0 offset:25616
	ds_read_b128 v[204:207], v0 offset:25680
	ds_read_b128 v[208:211], v0 offset:30224
	ds_read_b128 v[212:215], v0 offset:30288
	ds_read_b128 v[216:219], v0 offset:34832
	ds_read_b128 v[220:223], v0 offset:34896
	ds_read_b128 v[224:227], v0 offset:39440
	ds_read_b128 v[228:231], v0 offset:39504
	s_cmp_ge_u32 s88, s74
	s_cbranch_scc1 .Lmla_pvplain_0
	s_mul_i32 s91, s76, 0xac00
	s_waitcnt lgkmcnt(15)
	v_mfma_f32_32x32x16_bf16 v[64:79], v[84:87], v[80:83], v[64:79]
	v_readlane_b32 s90, v255, 11
	v_lshl_add_u32 v253, s88, v176, v166
	s_add_i32 m0, s91, s90
	s_nop 0
	global_load_lds_dwordx4 v253, s[12:13]
	s_waitcnt lgkmcnt(13)
	v_mfma_f32_32x32x16_bf16 v[48:63], v[92:95], v[80:83], v[48:63]
	s_waitcnt lgkmcnt(11)
	v_mfma_f32_32x32x16_bf16 v[32:47], v[100:103], v[80:83], v[32:47]
	v_lshl_add_u32 v253, s88, v177, v167
	s_add_i32 m0, s91, s85
	s_nop 0
	global_load_lds_dwordx4 v253, s[12:13]
	s_waitcnt lgkmcnt(9)
	v_mfma_f32_32x32x16_bf16 v[16:31], v[108:111], v[80:83], v[16:31]
	v_mfma_f32_32x32x16_bf16 v[64:79], v[88:91], v[6:9], v[64:79]
	v_lshl_add_u32 v253, s88, v178, v168
	s_add_i32 m0, s91, s72
	s_nop 0
	global_load_lds_dwordx4 v253, s[12:13]
	v_mfma_f32_32x32x16_bf16 v[48:63], v[96:99], v[6:9], v[48:63]
	v_mfma_f32_32x32x16_bf16 v[32:47], v[104:107], v[6:9], v[32:47]
	v_lshl_add_u32 v253, s88, v179, v169
	s_add_i32 m0, s91, s75
	s_nop 0
	global_load_lds_dwordx4 v253, s[12:13]
	s_waitcnt lgkmcnt(8)
	v_mfma_f32_32x32x16_bf16 v[16:31], v[186:189], v[6:9], v[16:31]
	s_waitcnt lgkmcnt(0)
	v_mfma_f32_32x32x16_bf16 v[64:79], v[200:203], v[10:13], v[64:79]
	v_lshl_add_u32 v253, s88, v180, v170
	s_add_i32 m0, s91, s1
	s_nop 0
	global_load_lds_dwordx4 v253, s[12:13]
	v_mfma_f32_32x32x16_bf16 v[48:63], v[208:211], v[10:13], v[48:63]
	v_mfma_f32_32x32x16_bf16 v[32:47], v[216:219], v[10:13], v[32:47]
	s_andn2_b64 vcc, exec, s[94:95]
	s_cbranch_vccnz .Lmla_a5_pv_0
	v_readlane_b32 s90, v255, 9
	v_lshl_add_u32 v253, s88, v181, v171
	s_add_i32 m0, s91, s90
	s_nop 0
	global_load_lds_dwordx4 v253, s[12:13]

; #define LAS __attribute__((address_space(3)))
; DI f32x16 zero16() { f32x16 z; for (int i = 0; i < 16; ++i) z[i] = 0.f; return z; }
; #define MFMA32(a, b, c) __builtin_amdgcn_mfma_f32_32x32x16_bf16((a), (b), (c), 0, 0, 0)
; DI void mla_s_softmax(const LAS unsigned char* base, int r, int h, bool is_diag, int lim, const bf16x8 (&qf)[12], f32x16 (&o)[4], float& m_run, float& l_run,
;                       bf16x8 (&pf0)[2], bf16x8 (&pf1)[2]) {
;     f32x16 s0 = zero16(), s1 = zero16();
;     const LAS unsigned char* kp = base + r * MLA_KROW + h * 16;
; #pragma unroll
;     for (int g = 0; g < 3; ++g) {
;         bf16x8 fa[4], fb[4];
; #pragma unroll
;         for (int j = 0; j < 4; ++j) { fa[j] = *(const LAS bf16x8*)(kp + (4 * g + j) * 32); fb[j] = *(const LAS bf16x8*)(kp + 32 * MLA_KROW + (4 * g + j) * 32); }
;         __builtin_amdgcn_sched_barrier(0);
; #pragma unroll
;         for (int j = 0; j < 4; ++j) { s0 = MFMA32(fa[j], qf[4 * g + j], s0); s1 = MFMA32(fb[j], qf[4 * g + j], s1); }
;         __builtin_amdgcn_sched_barrier(0);
;     }
.LBB0_639:
	s_add_i32 s73, s89, 0
	v_add3_u32 v0, s73, v174, v162
	s_andn2_b64 vcc, exec, s[2:3]
	s_branch .Lmla_splain_0
	s_cmp_ge_u32 s88, s74
	s_cbranch_scc1 .Lmla_splain_0
	s_mul_i32 s91, s76, 0xac00
	ds_read_b128 v[2:5], v0
	ds_read_b128 v[6:9], v0 offset:32
	ds_read_b128 v[10:13], v0 offset:12800
	ds_read_b128 v[186:189], v0 offset:12832
	ds_read_b128 v[190:193], v0 offset:64
	ds_read_b128 v[194:197], v0 offset:96
	ds_read_b128 v[198:201], v0 offset:12864
	ds_read_b128 v[202:205], v0 offset:12896
	ds_read_b128 v[206:209], v0 offset:128
	ds_read_b128 v[210:213], v0 offset:160
	ds_read_b128 v[214:217], v0 offset:12928
	ds_read_b128 v[218:221], v0 offset:12960
	ds_read_b128 v[222:225], v0 offset:192
	ds_read_b128 v[226:229], v0 offset:224
	ds_read_b128 v[230:233], v0 offset:12992
	ds_read_b128 v[234:237], v0 offset:13024
	s_waitcnt lgkmcnt(15)
	v_mfma_f32_32x32x16_bf16 v[96:111], v[2:5], v[112:115], 0
	v_readlane_b32 s90, v255, 11
	v_lshl_add_u32 v253, s88, v176, v166
	s_add_i32 m0, s91, s90
	s_nop 0
	global_load_lds_dwordx4 v253, s[12:13]
	s_waitcnt lgkmcnt(13)
	v_mfma_f32_32x32x16_bf16 v[80:95], v[10:13], v[112:115], 0
	v_mfma_f32_32x32x16_bf16 v[96:111], v[6:9], v[116:119], v[96:111]
	v_lshl_add_u32 v253, s88, v177, v167
	s_add_i32 m0, s91, s85
	s_nop 0
	global_load_lds_dwordx4 v253, s[12:13]
	s_waitcnt lgkmcnt(12)
	v_mfma_f32_32x32x16_bf16 v[80:95], v[186:189], v[116:119], v[80:95]
	s_waitcnt lgkmcnt(11)
	v_mfma_f32_32x32x16_bf16 v[96:111], v[190:193], v[120:123], v[96:111]
	v_lshl_add_u32 v253, s88, v178, v168
	s_add_i32 m0, s91, s72
	s_nop 0
	global_load_lds_dwordx4 v253, s[12:13]
	s_waitcnt lgkmcnt(9)
	v_mfma_f32_32x32x16_bf16 v[80:95], v[198:201], v[120:123], v[80:95]
	v_mfma_f32_32x32x16_bf16 v[96:111], v[194:197], v[124:127], v[96:111]
	v_lshl_add_u32 v253, s88, v179, v169
	s_add_i32 m0, s91, s75
	s_nop 0
	global_load_lds_dwordx4 v253, s[12:13]
	s_waitcnt lgkmcnt(8)
	v_mfma_f32_32x32x16_bf16 v[80:95], v[202:205], v[124:127], v[80:95]
	ds_read_b128 v[2:5], v0 offset:256
	ds_read_b128 v[6:9], v0 offset:288
	ds_read_b128 v[10:13], v0 offset:13056
	ds_read_b128 v[186:189], v0 offset:13088
	ds_read_b128 v[190:193], v0 offset:320
	ds_read_b128 v[194:197], v0 offset:352
	ds_read_b128 v[198:201], v0 offset:13120
	ds_read_b128 v[202:205], v0 offset:13152
	s_waitcnt lgkmcnt(8)
	v_mfma_f32_32x32x16_bf16 v[96:111], v[206:209], v[128:131], v[96:111]
	v_lshl_add_u32 v253, s88, v180, v170
	s_add_i32 m0, s91, s1
	s_nop 0
	global_load_lds_dwordx4 v253, s[12:13]
	v_mfma_f32_32x32x16_bf16 v[80:95], v[214:217], v[128:131], v[80:95]
	v_mfma_f32_32x32x16_bf16 v[96:111], v[210:213], v[132:135], v[96:111]
	s_andn2_b64 vcc, exec, s[94:95]
	s_cbranch_vccnz .Lmla_a5_s_0
	v_readlane_b32 s90, v255, 9
	v_lshl_add_u32 v253, s88, v181, v171
	s_add_i32 m0, s91, s90
	s_nop 0
	global_load_lds_dwordx4 v253, s[12:13]

; #define LAS __attribute__((address_space(3)))
; DI f32x16 zero16() { f32x16 z; for (int i = 0; i < 16; ++i) z[i] = 0.f; return z; }
; #define MFMA32(a, b, c) __builtin_amdgcn_mfma_f32_32x32x16_bf16((a), (b), (c), 0, 0, 0)
; DI void mla_s_softmax(const LAS unsigned char* base, int r, int h, bool is_diag, int lim, const bf16x8 (&qf)[12], f32x16 (&o)[4], float& m_run, float& l_run,
;                       bf16x8 (&pf0)[2], bf16x8 (&pf1)[2]) {
;     f32x16 s0 = zero16(), s1 = zero16();
;     const LAS unsigned char* kp = base + r * MLA_KROW + h * 16;
; #pragma unroll
;     for (int g = 0; g < 3; ++g) {
;         bf16x8 fa[4], fb[4];
; #pragma unroll
;         for (int j = 0; j < 4; ++j) { fa[j] = *(const LAS bf16x8*)(kp + (4 * g + j) * 32); fb[j] = *(const LAS bf16x8*)(kp + 32 * MLA_KROW + (4 * g + j) * 32); }
;         __builtin_amdgcn_sched_barrier(0);
; #pragma unroll
;         for (int j = 0; j < 4; ++j) { s0 = MFMA32(fa[j], qf[4 * g + j], s0); s1 = MFMA32(fb[j], qf[4 * g + j], s1); }
;         __builtin_amdgcn_sched_barrier(0);
;     }
.Lmla_splain_0:
	ds_read_b128 v[2:5], v0
	ds_read_b128 v[6:9], v0 offset:32
	ds_read_b128 v[10:13], v0 offset:12800
	ds_read_b128 v[186:189], v0 offset:12832
	ds_read_b128 v[190:193], v0 offset:64
	ds_read_b128 v[194:197], v0 offset:96
	ds_read_b128 v[198:201], v0 offset:12864
	ds_read_b128 v[202:205], v0 offset:12896
	ds_read_b128 v[206:209], v0 offset:128
	ds_read_b128 v[210:213], v0 offset:160
	ds_read_b128 v[214:217], v0 offset:12928
	ds_read_b128 v[218:221], v0 offset:12960
	ds_read_b128 v[222:225], v0 offset:192
	ds_read_b128 v[226:229], v0 offset:224
	ds_read_b128 v[230:233], v0 offset:12992
	ds_read_b128 v[234:237], v0 offset:13024
	s_cmp_lg_u32 s33, s77
	s_waitcnt lgkmcnt(15)
	v_mfma_f32_32x32x16_bf16 v[96:111], v[2:5], v[112:115], 0
	s_waitcnt lgkmcnt(13)
	v_mfma_f32_32x32x16_bf16 v[80:95], v[10:13], v[112:115], 0
	v_mfma_f32_32x32x16_bf16 v[96:111], v[6:9], v[116:119], v[96:111]
	s_waitcnt lgkmcnt(12)
	v_mfma_f32_32x32x16_bf16 v[80:95], v[186:189], v[116:119], v[80:95]
	s_waitcnt lgkmcnt(11)
	v_mfma_f32_32x32x16_bf16 v[96:111], v[190:193], v[120:123], v[96:111]
	s_waitcnt lgkmcnt(9)
	v_mfma_f32_32x32x16_bf16 v[80:95], v[198:201], v[120:123], v[80:95]
	v_mfma_f32_32x32x16_bf16 v[96:111], v[194:197], v[124:127], v[96:111]
	s_waitcnt lgkmcnt(8)
	v_mfma_f32_32x32x16_bf16 v[80:95], v[202:205], v[124:127], v[80:95]
	ds_read_b128 v[2:5], v0 offset:256
	ds_read_b128 v[6:9], v0 offset:288
	ds_read_b128 v[10:13], v0 offset:13056
	ds_read_b128 v[186:189], v0 offset:13088
	ds_read_b128 v[190:193], v0 offset:320
	ds_read_b128 v[194:197], v0 offset:352
	ds_read_b128 v[198:201], v0 offset:13120
	ds_read_b128 v[202:205], v0 offset:13152
	s_waitcnt lgkmcnt(8)
	v_mfma_f32_32x32x16_bf16 v[96:111], v[206:209], v[128:131], v[96:111]
	v_mfma_f32_32x32x16_bf16 v[80:95], v[214:217], v[128:131], v[80:95]
	v_mfma_f32_32x32x16_bf16 v[96:111], v[210:213], v[132:135], v[96:111]
	v_mfma_f32_32x32x16_bf16 v[80:95], v[218:221], v[132:135], v[80:95]
	v_mfma_f32_32x32x16_bf16 v[96:111], v[222:225], v[136:139], v[96:111]
	v_mfma_f32_32x32x16_bf16 v[80:95], v[230:233], v[136:139], v[80:95]
	v_mfma_f32_32x32x16_bf16 v[96:111], v[226:229], v[140:143], v[96:111]
	v_mfma_f32_32x32x16_bf16 v[80:95], v[234:237], v[140:143], v[80:95]
	s_waitcnt lgkmcnt(0)
	v_mfma_f32_32x32x16_bf16 v[96:111], v[2:5], v[144:147], v[96:111]
	v_mfma_f32_32x32x16_bf16 v[80:95], v[10:13], v[144:147], v[80:95]
	v_mfma_f32_32x32x16_bf16 v[96:111], v[6:9], v[148:151], v[96:111]
	v_mfma_f32_32x32x16_bf16 v[80:95], v[186:189], v[148:151], v[80:95]
	v_mfma_f32_32x32x16_bf16 v[96:111], v[190:193], v[152:155], v[96:111]
	v_mfma_f32_32x32x16_bf16 v[80:95], v[198:201], v[152:155], v[80:95]
	v_mfma_f32_32x32x16_bf16 v[96:111], v[194:197], v[156:159], v[96:111]
	v_mfma_f32_32x32x16_bf16 v[80:95], v[202:205], v[156:159], v[80:95]
	s_cbranch_scc1 .LBB0_641

; #define LAS __attribute__((address_space(3)))
; #define MFMA32(a, b, c) __builtin_amdgcn_mfma_f32_32x32x16_bf16((a), (b), (c), 0, 0, 0)
; DI void mla_pv(const LAS unsigned char* base, int r, int h, const bf16x8 (&pf0)[2], const bf16x8 (&pf1)[2], f32x16 (&o)[4]) {
;     const LAS unsigned char* vp = base + MLA_KBYTES + r * MLA_VROW + h * 32;
; #pragma unroll
;     for (int s = 0; s < 2; ++s) {
;         bf16x8 va[4], vb[4];
; #pragma unroll
;         for (int dt = 0; dt < 4; ++dt) { va[dt] = *(const LAS bf16x8*)(vp + dt * 32 * MLA_VROW + s * 16); vb[dt] = *(const LAS bf16x8*)(vp + dt * 32 * MLA_VROW + 64 + s * 16); }
;         __builtin_amdgcn_sched_barrier(0);
; #pragma unroll
;         for (int dt = 0; dt < 4; ++dt) o[dt] = MFMA32(va[dt], pf0[s], o[dt]);
; #pragma unroll
;         for (int dt = 0; dt < 4; ++dt) o[dt] = MFMA32(vb[dt], pf1[s], o[dt]);
;         __builtin_amdgcn_sched_barrier(0);
;     }
.LBB0_737:
	s_cmp_lg_u32 s88, 0
	s_cselect_b64 s[90:91], -1, 0
	s_and_b64 s[90:91], s[78:79], s[90:91]
	s_cmp_lt_i32 s100, s33
	s_cselect_b64 vcc, -1, 0
	s_and_b64 s[90:91], s[90:91], vcc
	s_andn2_b64 vcc, exec, s[90:91]
	s_mul_i32 s89, s87, 0xac00
	s_cbranch_vccnz .LBB0_740
	s_add_i32 s90, s89, 0xffff5400
	s_cmp_lg_u32 s87, 0
	s_cselect_b32 s87, s90, 0x15800
	v_add_u32_e32 v0, s87, v182
	ds_read_b128 v[84:87], v0 offset:25600
	ds_read_b128 v[88:91], v0 offset:25664
	ds_read_b128 v[92:95], v0 offset:30208
	ds_read_b128 v[96:99], v0 offset:30272
	ds_read_b128 v[100:103], v0 offset:34816
	ds_read_b128 v[104:107], v0 offset:34880
	ds_read_b128 v[108:111], v0 offset:39424
	ds_read_b128 v[186:189], v0 offset:39488
	ds_read_b128 v[200:203], v0 offset:25616
	ds_read_b128 v[204:207], v0 offset:25680
	ds_read_b128 v[208:211], v0 offset:30224
	ds_read_b128 v[212:215], v0 offset:30288
	ds_read_b128 v[216:219], v0 offset:34832
	ds_read_b128 v[220:223], v0 offset:34896
	ds_read_b128 v[224:227], v0 offset:39440
	ds_read_b128 v[228:231], v0 offset:39504
	s_cmp_ge_u32 s77, s73
	s_cbranch_scc1 .Lmla_pvplain_1
	s_mul_i32 s91, s76, 0xac00
	s_waitcnt lgkmcnt(15)
	v_mfma_f32_32x32x16_bf16 v[64:79], v[84:87], v[80:83], v[64:79]
	v_readlane_b32 s90, v255, 9
	v_lshl_add_u32 v253, s98, v176, v166
	s_add_i32 m0, s91, s90
	s_nop 0
	global_load_lds_dwordx4 v253, s[12:13]
	s_waitcnt lgkmcnt(13)
	v_mfma_f32_32x32x16_bf16 v[48:63], v[92:95], v[80:83], v[48:63]
	s_waitcnt lgkmcnt(11)
	v_mfma_f32_32x32x16_bf16 v[32:47], v[100:103], v[80:83], v[32:47]
	v_lshl_add_u32 v253, s98, v177, v167
	s_add_i32 m0, s91, s75
	s_nop 0
	global_load_lds_dwordx4 v253, s[12:13]
	s_waitcnt lgkmcnt(9)
	v_mfma_f32_32x32x16_bf16 v[16:31], v[108:111], v[80:83], v[16:31]
	v_mfma_f32_32x32x16_bf16 v[64:79], v[88:91], v[6:9], v[64:79]
	v_readlane_b32 s90, v255, 11
	v_lshl_add_u32 v253, s98, v178, v168
	s_add_i32 m0, s91, s90
	s_nop 0
	global_load_lds_dwordx4 v253, s[12:13]
	v_mfma_f32_32x32x16_bf16 v[48:63], v[96:99], v[6:9], v[48:63]
	v_mfma_f32_32x32x16_bf16 v[32:47], v[104:107], v[6:9], v[32:47]
	v_readlane_b32 s90, v255, 49
	v_lshl_add_u32 v253, s98, v179, v169
	s_add_i32 m0, s91, s90
	s_nop 0
	global_load_lds_dwordx4 v253, s[12:13]
	s_waitcnt lgkmcnt(8)
	v_mfma_f32_32x32x16_bf16 v[16:31], v[186:189], v[6:9], v[16:31]
	s_waitcnt lgkmcnt(0)
	v_mfma_f32_32x32x16_bf16 v[64:79], v[200:203], v[10:13], v[64:79]
	v_lshl_add_u32 v253, s98, v180, v170
	s_add_i32 m0, s91, s86
	s_nop 0
	global_load_lds_dwordx4 v253, s[12:13]
	v_mfma_f32_32x32x16_bf16 v[48:63], v[208:211], v[10:13], v[48:63]
	v_mfma_f32_32x32x16_bf16 v[32:47], v[216:219], v[10:13], v[32:47]
	s_andn2_b64 vcc, exec, s[94:95]
	s_cbranch_vccnz .Lmla_a5_pv_1
	v_lshl_add_u32 v253, s98, v181, v171
	s_add_i32 m0, s91, s72
	s_nop 0
	global_load_lds_dwordx4 v253, s[12:13]

; #define LAS __attribute__((address_space(3)))
; DI f32x16 zero16() { f32x16 z; for (int i = 0; i < 16; ++i) z[i] = 0.f; return z; }
; #define MFMA32(a, b, c) __builtin_amdgcn_mfma_f32_32x32x16_bf16((a), (b), (c), 0, 0, 0)
; DI void mla_s_softmax(const LAS unsigned char* base, int r, int h, bool is_diag, int lim, const bf16x8 (&qf)[12], f32x16 (&o)[4], float& m_run, float& l_run,
;                       bf16x8 (&pf0)[2], bf16x8 (&pf1)[2]) {
;     f32x16 s0 = zero16(), s1 = zero16();
;     const LAS unsigned char* kp = base + r * MLA_KROW + h * 16;
; #pragma unroll
;     for (int g = 0; g < 3; ++g) {
;         bf16x8 fa[4], fb[4];
; #pragma unroll
;         for (int j = 0; j < 4; ++j) { fa[j] = *(const LAS bf16x8*)(kp + (4 * g + j) * 32); fb[j] = *(const LAS bf16x8*)(kp + 32 * MLA_KROW + (4 * g + j) * 32); }
;         __builtin_amdgcn_sched_barrier(0);
; #pragma unroll
;         for (int j = 0; j < 4; ++j) { s0 = MFMA32(fa[j], qf[4 * g + j], s0); s1 = MFMA32(fb[j], qf[4 * g + j], s1); }
;         __builtin_amdgcn_sched_barrier(0);
;     }
.LBB0_741:
	s_add_i32 s87, s89, 0
	v_add3_u32 v0, s87, v175, v162
	s_andn2_b64 vcc, exec, s[2:3]
	s_branch .Lmla_splain_1
	s_cmp_ge_u32 s77, s73
	s_cbranch_scc1 .Lmla_splain_1
	s_mul_i32 s91, s76, 0xac00
	ds_read_b128 v[2:5], v0
	ds_read_b128 v[6:9], v0 offset:32
	ds_read_b128 v[10:13], v0 offset:12800
	ds_read_b128 v[186:189], v0 offset:12832
	ds_read_b128 v[190:193], v0 offset:64
	ds_read_b128 v[194:197], v0 offset:96
	ds_read_b128 v[198:201], v0 offset:12864
	ds_read_b128 v[202:205], v0 offset:12896
	ds_read_b128 v[206:209], v0 offset:128
	ds_read_b128 v[210:213], v0 offset:160
	ds_read_b128 v[214:217], v0 offset:12928
	ds_read_b128 v[218:221], v0 offset:12960
	ds_read_b128 v[222:225], v0 offset:192
	ds_read_b128 v[226:229], v0 offset:224
	ds_read_b128 v[230:233], v0 offset:12992
	ds_read_b128 v[234:237], v0 offset:13024
	s_waitcnt lgkmcnt(15)
	v_mfma_f32_32x32x16_bf16 v[96:111], v[2:5], v[112:115], 0
	v_readlane_b32 s90, v255, 9
	v_lshl_add_u32 v253, s98, v176, v166
	s_add_i32 m0, s91, s90
	s_nop 0
	global_load_lds_dwordx4 v253, s[12:13]
	s_waitcnt lgkmcnt(13)
	v_mfma_f32_32x32x16_bf16 v[80:95], v[10:13], v[112:115], 0
	v_mfma_f32_32x32x16_bf16 v[96:111], v[6:9], v[116:119], v[96:111]
	v_lshl_add_u32 v253, s98, v177, v167
	s_add_i32 m0, s91, s75
	s_nop 0
	global_load_lds_dwordx4 v253, s[12:13]
	s_waitcnt lgkmcnt(12)
	v_mfma_f32_32x32x16_bf16 v[80:95], v[186:189], v[116:119], v[80:95]
	s_waitcnt lgkmcnt(11)
	v_mfma_f32_32x32x16_bf16 v[96:111], v[190:193], v[120:123], v[96:111]
	v_readlane_b32 s90, v255, 11
	v_lshl_add_u32 v253, s98, v178, v168
	s_add_i32 m0, s91, s90
	s_nop 0
	global_load_lds_dwordx4 v253, s[12:13]
	s_waitcnt lgkmcnt(9)
	v_mfma_f32_32x32x16_bf16 v[80:95], v[198:201], v[120:123], v[80:95]
	v_mfma_f32_32x32x16_bf16 v[96:111], v[194:197], v[124:127], v[96:111]
	v_readlane_b32 s90, v255, 49
	v_lshl_add_u32 v253, s98, v179, v169
	s_add_i32 m0, s91, s90
	s_nop 0
	global_load_lds_dwordx4 v253, s[12:13]
	s_waitcnt lgkmcnt(8)
	v_mfma_f32_32x32x16_bf16 v[80:95], v[202:205], v[124:127], v[80:95]
	ds_read_b128 v[2:5], v0 offset:256
	ds_read_b128 v[6:9], v0 offset:288
	ds_read_b128 v[10:13], v0 offset:13056
	ds_read_b128 v[186:189], v0 offset:13088
	ds_read_b128 v[190:193], v0 offset:320
	ds_read_b128 v[194:197], v0 offset:352
	ds_read_b128 v[198:201], v0 offset:13120
	ds_read_b128 v[202:205], v0 offset:13152
	s_waitcnt lgkmcnt(8)
	v_mfma_f32_32x32x16_bf16 v[96:111], v[206:209], v[128:131], v[96:111]
	v_lshl_add_u32 v253, s98, v180, v170
	s_add_i32 m0, s91, s86
	s_nop 0
	global_load_lds_dwordx4 v253, s[12:13]
	v_mfma_f32_32x32x16_bf16 v[80:95], v[214:217], v[128:131], v[80:95]
	v_mfma_f32_32x32x16_bf16 v[96:111], v[210:213], v[132:135], v[96:111]
	s_andn2_b64 vcc, exec, s[94:95]
	s_cbranch_vccnz .Lmla_a5_s_1
	v_lshl_add_u32 v253, s98, v181, v171
	s_add_i32 m0, s91, s72
	s_nop 0
	global_load_lds_dwordx4 v253, s[12:13]

; #define LAS __attribute__((address_space(3)))
; DI f32x16 zero16() { f32x16 z; for (int i = 0; i < 16; ++i) z[i] = 0.f; return z; }
; #define MFMA32(a, b, c) __builtin_amdgcn_mfma_f32_32x32x16_bf16((a), (b), (c), 0, 0, 0)
; DI void mla_s_softmax(const LAS unsigned char* base, int r, int h, bool is_diag, int lim, const bf16x8 (&qf)[12], f32x16 (&o)[4], float& m_run, float& l_run,
;                       bf16x8 (&pf0)[2], bf16x8 (&pf1)[2]) {
;     f32x16 s0 = zero16(), s1 = zero16();
;     const LAS unsigned char* kp = base + r * MLA_KROW + h * 16;
; #pragma unroll
;     for (int g = 0; g < 3; ++g) {
;         bf16x8 fa[4], fb[4];
; #pragma unroll
;         for (int j = 0; j < 4; ++j) { fa[j] = *(const LAS bf16x8*)(kp + (4 * g + j) * 32); fb[j] = *(const LAS bf16x8*)(kp + 32 * MLA_KROW + (4 * g + j) * 32); }
;         __builtin_amdgcn_sched_barrier(0);
; #pragma unroll
;         for (int j = 0; j < 4; ++j) { s0 = MFMA32(fa[j], qf[4 * g + j], s0); s1 = MFMA32(fb[j], qf[4 * g + j], s1); }
;         __builtin_amdgcn_sched_barrier(0);
;     }
.Lmla_splain_1:
	ds_read_b128 v[2:5], v0
	ds_read_b128 v[6:9], v0 offset:32
	ds_read_b128 v[10:13], v0 offset:12800
	ds_read_b128 v[186:189], v0 offset:12832
	ds_read_b128 v[190:193], v0 offset:64
	ds_read_b128 v[194:197], v0 offset:96
	ds_read_b128 v[198:201], v0 offset:12864
	ds_read_b128 v[202:205], v0 offset:12896
	ds_read_b128 v[206:209], v0 offset:128
	ds_read_b128 v[210:213], v0 offset:160
	ds_read_b128 v[214:217], v0 offset:12928
	ds_read_b128 v[218:221], v0 offset:12960
	ds_read_b128 v[222:225], v0 offset:192
	ds_read_b128 v[226:229], v0 offset:224
	ds_read_b128 v[230:233], v0 offset:12992
	ds_read_b128 v[234:237], v0 offset:13024
	s_cmp_lg_u32 s33, s99
	s_waitcnt lgkmcnt(15)
	v_mfma_f32_32x32x16_bf16 v[96:111], v[2:5], v[112:115], 0
	s_waitcnt lgkmcnt(13)
	v_mfma_f32_32x32x16_bf16 v[80:95], v[10:13], v[112:115], 0
	v_mfma_f32_32x32x16_bf16 v[96:111], v[6:9], v[116:119], v[96:111]
	s_waitcnt lgkmcnt(12)
	v_mfma_f32_32x32x16_bf16 v[80:95], v[186:189], v[116:119], v[80:95]
	s_waitcnt lgkmcnt(11)
	v_mfma_f32_32x32x16_bf16 v[96:111], v[190:193], v[120:123], v[96:111]
	s_waitcnt lgkmcnt(9)
	v_mfma_f32_32x32x16_bf16 v[80:95], v[198:201], v[120:123], v[80:95]
	v_mfma_f32_32x32x16_bf16 v[96:111], v[194:197], v[124:127], v[96:111]
	s_waitcnt lgkmcnt(8)
	v_mfma_f32_32x32x16_bf16 v[80:95], v[202:205], v[124:127], v[80:95]
	ds_read_b128 v[2:5], v0 offset:256
	ds_read_b128 v[6:9], v0 offset:288
	ds_read_b128 v[10:13], v0 offset:13056
	ds_read_b128 v[186:189], v0 offset:13088
	ds_read_b128 v[190:193], v0 offset:320
	ds_read_b128 v[194:197], v0 offset:352
	ds_read_b128 v[198:201], v0 offset:13120
	ds_read_b128 v[202:205], v0 offset:13152
	s_waitcnt lgkmcnt(8)
	v_mfma_f32_32x32x16_bf16 v[96:111], v[206:209], v[128:131], v[96:111]
	v_mfma_f32_32x32x16_bf16 v[80:95], v[214:217], v[128:131], v[80:95]
	v_mfma_f32_32x32x16_bf16 v[96:111], v[210:213], v[132:135], v[96:111]
	v_mfma_f32_32x32x16_bf16 v[80:95], v[218:221], v[132:135], v[80:95]
	v_mfma_f32_32x32x16_bf16 v[96:111], v[222:225], v[136:139], v[96:111]
	v_mfma_f32_32x32x16_bf16 v[80:95], v[230:233], v[136:139], v[80:95]
	v_mfma_f32_32x32x16_bf16 v[96:111], v[226:229], v[140:143], v[96:111]
	v_mfma_f32_32x32x16_bf16 v[80:95], v[234:237], v[140:143], v[80:95]
	s_waitcnt lgkmcnt(0)
	v_mfma_f32_32x32x16_bf16 v[96:111], v[2:5], v[144:147], v[96:111]
	v_mfma_f32_32x32x16_bf16 v[80:95], v[10:13], v[144:147], v[80:95]
	v_mfma_f32_32x32x16_bf16 v[96:111], v[6:9], v[148:151], v[96:111]
	v_mfma_f32_32x32x16_bf16 v[80:95], v[186:189], v[148:151], v[80:95]
	v_mfma_f32_32x32x16_bf16 v[96:111], v[190:193], v[152:155], v[96:111]
	v_mfma_f32_32x32x16_bf16 v[80:95], v[198:201], v[152:155], v[80:95]
	v_mfma_f32_32x32x16_bf16 v[96:111], v[194:197], v[156:159], v[96:111]
	v_mfma_f32_32x32x16_bf16 v[80:95], v[202:205], v[156:159], v[80:95]
	s_cbranch_scc1 .LBB0_743
